# mix0 dynamic queue interleaved: two attention tiles then one gmlp tile for the first 2304 entries, then 512 attention, the last 256 gmlp tiles fill the tail
# speedup vs baseline: 1.0055x; 1.0030x over previous
.LBB0_248:
	s_or_b64 exec, exec, s[0:1]
	s_cmpk_gt_i32 s2, 0xbff
	v_lshlrev_b32_e32 v156, 9, v131
	v_lshlrev_b32_e32 v159, 2, v134
	v_lshlrev_b32_e32 v158, 5, v131
	s_waitcnt lgkmcnt(0)
	s_barrier
	s_cbranch_scc1 .LBB0_261
	v_lshlrev_b32_e32 v4, 13, v135
	v_lshl_add_u32 v6, v134, 3, v138
	v_lshl_or_b32 v8, v134, 11, v4
	v_lshlrev_b32_e32 v10, 5, v138
	v_or3_b32 v77, v4, v137, v10
	v_lshl_or_b32 v102, v6, 2, v8
	v_add_u32_e32 v10, 0x60, v6
	v_add_u32_e32 v6, 0x70, v6
	v_and_b32_e32 v10, 0x7f, v10
	v_and_b32_e32 v6, 0x7f, v6
	v_lshl_or_b32 v103, v10, 2, v8
	v_lshl_or_b32 v104, v6, 2, v8
	v_add_u32_e32 v8, 8, v133
	v_and_b32_e32 v8, 0x78, v8
	v_lshlrev_b32_e32 v6, 9, v136
	v_lshlrev_b32_e32 v8, 2, v8
	v_or3_b32 v106, v4, v6, v8
	v_add_u32_e32 v8, 16, v133
	v_and_b32_e32 v8, 0x78, v8
	v_lshlrev_b32_e32 v6, 9, v132
	v_lshlrev_b32_e32 v8, 2, v8
	v_or3_b32 v108, v4, v6, v8
	v_add_u32_e32 v8, 24, v133
	v_xor_b32_e32 v0, v128, v131
	v_and_b32_e32 v8, 0x78, v8
	v_lshlrev_b32_e32 v1, 3, v0
	v_lshlrev_b32_e32 v6, 9, v130
	v_lshlrev_b32_e32 v8, 2, v8
	v_and_b32_e32 v0, 56, v1
	s_movk_i32 s0, 0x1e0
	v_or3_b32 v110, v4, v6, v8
	v_and_b32_e32 v6, 0x78, v1
	v_xor_b32_e32 v1, 1, v134
	v_and_or_b32 v2, v153, s0, v138
	v_cmp_gt_u32_e64 s[0:1], v1, v134
	v_xor_b32_e32 v1, 2, v134
	v_cmp_gt_u32_e64 s[22:23], v1, v134
	v_xor_b32_e32 v1, 3, v134
	v_cmp_gt_u32_e64 s[4:5], v1, v134
	v_bitop3_b32 v1, v134, v131, 15 bitop3:0x78
	v_lshlrev_b32_e32 v120, 4, v1
	v_bitop3_b32 v1, v134, v138, 4 bitop3:0x36
	v_lshlrev_b32_e32 v121, 4, v1
	v_bitop3_b32 v1, v134, v138, 8 bitop3:0x36
	v_lshlrev_b32_e32 v122, 4, v1
	v_bitop3_b32 v1, v134, v138, 12 bitop3:0x36
	v_lshlrev_b32_e32 v123, 4, v1
	v_xor_b32_e32 v1, v134, v131
	v_lshlrev_b32_e32 v1, 3, v1
	v_and_b32_e32 v124, 0x70, v1
	v_bitop3_b32 v1, v134, v131, 4 bitop3:0x36
	v_lshlrev_b32_e32 v1, 3, v1
	v_and_b32_e32 v125, 0x70, v1
	v_bitop3_b32 v1, v134, v131, 8 bitop3:0x36
	v_lshlrev_b32_e32 v1, 3, v1
	v_and_b32_e32 v126, 0x70, v1
	v_bitop3_b32 v1, v134, v131, 12 bitop3:0x36
	v_mov_b32_e32 v72, 0
	v_lshlrev_b32_e32 v1, 3, v1
	v_and_b32_e32 v127, 0x70, v1
	v_mul_u32_u24_e32 v1, 0x210, v138
	s_movk_i32 s8, 0x2100
	v_and_b32_e32 v10, 0x7f00, v158
	v_mov_b32_e32 v11, v72
	v_mad_u32_u24 v1, v135, s8, v1
	s_movk_i32 s8, 0xfe10
	v_lshl_add_u64 v[12:13], s[50:51], 0, v[10:11]
	v_lshlrev_b32_e32 v14, 1, v0
	v_mov_b32_e32 v15, v72
	s_add_u32 s30, s50, 0x9a00000
	v_lshlrev_b32_e32 v9, 5, v135
	v_mad_i32_i24 v16, v138, s8, v1
	v_lshl_add_u64 v[12:13], v[12:13], 0, v[14:15]
	s_mov_b64 s[8:9], 0x1080000
	v_lshl_add_u64 v[10:11], s[48:49], 0, v[10:11]
	s_addc_u32 s31, s51, 0
	v_bitop3_b32 v3, v128, v139, 3 bitop3:0x6c
	v_or_b32_e32 v4, 16, v9
	v_lshl_add_u64 v[78:79], v[12:13], 0, s[8:9]
	v_lshl_add_u64 v[10:11], v[10:11], 0, v[14:15]
	s_mov_b64 s[8:9], 0x2000000
	s_add_u32 s34, s50, 0xba00000
	v_lshlrev_b32_e32 v75, 7, v138
	v_lshlrev_b32_e32 v3, 4, v3
	v_lshlrev_b32_e32 v5, 7, v2
	v_lshlrev_b32_e32 v7, 4, v152
	v_lshlrev_b32_e32 v2, 3, v138
	v_or_b32_e32 v105, v134, v9
	v_or_b32_e32 v107, v136, v9
	v_or_b32_e32 v109, v132, v9
	v_or_b32_e32 v111, v130, v9
	v_or_b32_e32 v74, v4, v134
	v_or_b32_e32 v112, v136, v4
	v_or_b32_e32 v113, v132, v4
	v_or_b32_e32 v114, v130, v4
	v_lshlrev_b32_e32 v76, 4, v135
	v_lshlrev_b32_e32 v4, 3, v134
	v_and_b32_e32 v8, 0x7f000, v156
	v_mov_b32_e32 v118, 0x10000
	v_and_b32_e32 v9, 48, v131
	v_mul_u32_u24_e32 v17, 0x210, v134
	v_lshl_add_u64 v[80:81], v[10:11], 0, s[8:9]
	s_addc_u32 s35, s51, 0
	v_lshlrev_b32_e32 v10, 1, v6
	v_mov_b32_e32 v11, v72
	v_or_b32_e32 v115, v76, v138
	v_lshlrev_b32_e32 v116, 8, v138
	v_and_b32_e32 v117, 8, v4
	s_mov_b32 s29, 0
	v_cmp_eq_u32_e64 s[6:7], 0, v141
	v_lshl_or_b32 v119, v135, 2, v118
	v_lshl_add_u64 v[82:83], s[34:35], 0, v[10:11]
	s_xor_b32 s33, s2, 63
	s_mov_b64 s[38:39], 0x2000
	v_add_u32_e32 v141, 0x1000, v129
	s_mov_b64 s[46:47], 0x4000
	v_add_u32_e32 v142, 0x2000, v129
	s_mov_b64 s[52:53], 0x6000
	v_add_u32_e32 v143, 0x3000, v129
	v_or_b32_e32 v144, 0x4000, v129
	v_add_u32_e32 v145, 0x5000, v129
	v_add_u32_e32 v146, 0x6000, v129
	v_add_u32_e32 v147, 0x7000, v129
	s_mov_b64 s[56:57], 0x80
	v_or_b32_e32 v148, 0x8000, v129
	s_mov_b64 s[58:59], 0x2080
	v_add_u32_e32 v150, 0x9000, v129
	s_mov_b64 s[60:61], 0x4080
	v_add_u32_e32 v151, 0xa000, v129
	s_mov_b64 s[64:65], 0x6080
	v_add_u32_e32 v160, 0xb000, v129
	v_or_b32_e32 v161, 0xc000, v129
	v_add_u32_e32 v162, 0xd000, v129
	v_add_u32_e32 v163, 0xe000, v129
	v_add_u32_e32 v164, 0xf000, v129
	v_add_u32_e32 v165, v3, v5
	v_add_u32_e32 v166, v3, v75
	v_add_u32_e32 v167, v7, v5
	v_add_u32_e32 v168, v7, v75
	s_movk_i32 s84, 0x7fff
	s_mov_b32 s85, 0x7060302
	v_lshlrev_b32_e32 v84, 1, v4
	v_lshlrev_b32_e32 v86, 1, v6
	s_mov_b64 s[66:67], 0x8000
	s_mov_b64 s[70:71], 0x10000
	s_mov_b64 s[72:73], 0x18000
	v_lshlrev_b32_e32 v88, 1, v8
	v_lshlrev_b32_e32 v90, 1, v0
	s_mov_b64 s[74:75], 0x40000
	s_mov_b64 s[76:77], 0x80000
	s_mov_b64 s[78:79], 0xc0000
	s_mov_b32 s86, 0xc3200000
	v_add_u32_e32 v169, v1, v9
	v_add_u32_e32 v170, v16, v17
	s_mov_b32 s87, 0x5a00000
	v_add_u32_e32 v171, 0x400, v102
	v_lshlrev_b32_e32 v92, 1, v2
	v_mbcnt_hi_u32_b32 v172, -1, v155
	s_mov_b32 s93, s2
	v_readfirstlane_b32 s99, v129
	s_branch .Lmy_m0_map

.Lmy_m0_rd:
	s_barrier
	v_mov_b32_e32 v101, 0x10018
	ds_read_b32 v100, v101
	s_waitcnt lgkmcnt(0)
	v_readfirstlane_b32 s93, v100
.Lmy_m0_map:
	s_cmpk_lt_i32 s93, 0xc00
	s_cbranch_scc0 .LBB0_261
	s_cmpk_ge_i32 s93, 0x900
	s_cbranch_scc1 .Lmy_m0_hi
	s_mul_i32 s98, s93, 0xaaab
	s_lshr_b32 s98, s98, 17
	s_mul_i32 s100, s98, 3
	s_sub_i32 s100, s93, s100
	s_lshl_b32 s88, s98, 1
	s_add_i32 s88, s88, s100
	s_add_i32 s98, s98, 0x800
	s_cmp_eq_u32 s100, 2
	s_cselect_b32 s88, s98, s88
	s_branch .Lmy_m0_mapped
.Lmy_m0_hi:
	s_sub_i32 s88, s93, 0x300
	s_cmpk_ge_i32 s93, 0xb00
	s_cbranch_scc0 .Lmy_m0_mapped
	s_mov_b32 s88, s93
.Lmy_m0_mapped:
	s_xor_b32 s33, s88, 63
